# hand-written adaLN modulation routine (16-column items, 64 loads in flight per thread) replaces hipcc's 64-column loop in phase 0
# speedup vs baseline: 1.0456x; 1.0236x over previous
.LBB0_686:
	v_readlane_b32 s2, v227, 58
	v_readlane_b32 s3, v227, 59
	v_readlane_b32 s20, v224, 32
	s_andn2_b64 vcc, exec, s[2:3]
	v_and_b32_e32 v14, 63, v15
	s_mov_b32 s88, 0x800000
	s_mov_b64 s[68:69], 0x40100
	v_readlane_b32 s21, v224, 33
	s_branch .Lada2
.Lada2:
	s_waitcnt vmcnt(0) lgkmcnt(0)
	s_barrier
	v_readlane_b32 s40, v224, 34
	v_readlane_b32 s41, v224, 35
	s_load_dwordx4 s[44:47], s[40:41], 0x28
	s_load_dwordx4 s[48:51], s[40:41], 0x38
	s_load_dwordx2 s[42:43], s[40:41], 0x1b0
	v_lshlrev_b32_e32 v2, 2, v131
	v_add_u32_e32 v3, 0x1000, v2
	v_add_u32_e32 v4, 0x2000, v2
	v_add_u32_e32 v5, 0x3000, v2
	s_waitcnt lgkmcnt(0)
	global_load_dword v20, v2, s[46:47] offset:0
	global_load_dword v21, v2, s[46:47] offset:1024
	global_load_dword v22, v2, s[46:47] offset:2048
	global_load_dword v23, v2, s[46:47] offset:3072
	global_load_dword v24, v2, s[44:45] offset:0
	global_load_dword v25, v2, s[44:45] offset:1024
	global_load_dword v26, v2, s[44:45] offset:2048
	global_load_dword v27, v2, s[44:45] offset:3072
	global_load_dword v28, v3, s[44:45] offset:0
	global_load_dword v29, v3, s[44:45] offset:1024
	global_load_dword v30, v3, s[44:45] offset:2048
	global_load_dword v31, v3, s[44:45] offset:3072
	global_load_dword v32, v4, s[44:45] offset:0
	global_load_dword v33, v4, s[44:45] offset:1024
	global_load_dword v34, v4, s[44:45] offset:2048
	global_load_dword v35, v4, s[44:45] offset:3072
	global_load_dword v36, v5, s[44:45] offset:0
	global_load_dword v37, v5, s[44:45] offset:1024
	global_load_dword v38, v5, s[44:45] offset:2048
	global_load_dword v39, v5, s[44:45] offset:3072
	s_waitcnt vmcnt(0)
	v_mul_f32_e32 v6, 0xbfb8aa3b, v20
	v_exp_f32_e32 v6, v6
	s_nop 0
	v_add_f32_e32 v6, 1.0, v6
	v_rcp_f32_e32 v6, v6
	s_nop 0
	v_mul_f32_e32 v6, v20, v6
	ds_write_b32 v2, v6 offset:0
	v_mul_f32_e32 v6, 0xbfb8aa3b, v21
	v_exp_f32_e32 v6, v6
	s_nop 0
	v_add_f32_e32 v6, 1.0, v6
	v_rcp_f32_e32 v6, v6
	s_nop 0
	v_mul_f32_e32 v6, v21, v6
	ds_write_b32 v2, v6 offset:1024
	v_mul_f32_e32 v6, 0xbfb8aa3b, v22
	v_exp_f32_e32 v6, v6
	s_nop 0
	v_add_f32_e32 v6, 1.0, v6
	v_rcp_f32_e32 v6, v6
	s_nop 0
	v_mul_f32_e32 v6, v22, v6
	ds_write_b32 v2, v6 offset:2048
	v_mul_f32_e32 v6, 0xbfb8aa3b, v23
	v_exp_f32_e32 v6, v6
	s_nop 0
	v_add_f32_e32 v6, 1.0, v6
	v_rcp_f32_e32 v6, v6
	s_nop 0
	v_mul_f32_e32 v6, v23, v6
	ds_write_b32 v2, v6 offset:3072
	v_mul_f32_e32 v6, 0xbfb8aa3b, v24
	v_exp_f32_e32 v6, v6
	s_nop 0
	v_add_f32_e32 v6, 1.0, v6
	v_rcp_f32_e32 v6, v6
	s_nop 0
	v_mul_f32_e32 v6, v24, v6
	ds_write_b32 v2, v6 offset:4096
	v_mul_f32_e32 v6, 0xbfb8aa3b, v25
	v_exp_f32_e32 v6, v6
	s_nop 0
	v_add_f32_e32 v6, 1.0, v6
	v_rcp_f32_e32 v6, v6
	s_nop 0
	v_mul_f32_e32 v6, v25, v6
	ds_write_b32 v2, v6 offset:5120
	v_mul_f32_e32 v6, 0xbfb8aa3b, v26
	v_exp_f32_e32 v6, v6
	s_nop 0
	v_add_f32_e32 v6, 1.0, v6
	v_rcp_f32_e32 v6, v6
	s_nop 0
	v_mul_f32_e32 v6, v26, v6
	ds_write_b32 v2, v6 offset:6144
	v_mul_f32_e32 v6, 0xbfb8aa3b, v27
	v_exp_f32_e32 v6, v6
	s_nop 0
	v_add_f32_e32 v6, 1.0, v6
	v_rcp_f32_e32 v6, v6
	s_nop 0
	v_mul_f32_e32 v6, v27, v6
	ds_write_b32 v2, v6 offset:7168
	v_mul_f32_e32 v6, 0xbfb8aa3b, v28
	v_exp_f32_e32 v6, v6
	s_nop 0
	v_add_f32_e32 v6, 1.0, v6
	v_rcp_f32_e32 v6, v6
	s_nop 0
	v_mul_f32_e32 v6, v28, v6
	ds_write_b32 v2, v6 offset:8192
	v_mul_f32_e32 v6, 0xbfb8aa3b, v29
	v_exp_f32_e32 v6, v6
	s_nop 0
	v_add_f32_e32 v6, 1.0, v6
	v_rcp_f32_e32 v6, v6
	s_nop 0
	v_mul_f32_e32 v6, v29, v6
	ds_write_b32 v2, v6 offset:9216
	v_mul_f32_e32 v6, 0xbfb8aa3b, v30
	v_exp_f32_e32 v6, v6
	s_nop 0
	v_add_f32_e32 v6, 1.0, v6
	v_rcp_f32_e32 v6, v6
	s_nop 0
	v_mul_f32_e32 v6, v30, v6
	ds_write_b32 v2, v6 offset:10240
	v_mul_f32_e32 v6, 0xbfb8aa3b, v31
	v_exp_f32_e32 v6, v6
	s_nop 0
	v_add_f32_e32 v6, 1.0, v6
	v_rcp_f32_e32 v6, v6
	s_nop 0
	v_mul_f32_e32 v6, v31, v6
	ds_write_b32 v2, v6 offset:11264
	v_mul_f32_e32 v6, 0xbfb8aa3b, v32
	v_exp_f32_e32 v6, v6
	s_nop 0
	v_add_f32_e32 v6, 1.0, v6
	v_rcp_f32_e32 v6, v6
	s_nop 0
	v_mul_f32_e32 v6, v32, v6
	ds_write_b32 v2, v6 offset:12288
	v_mul_f32_e32 v6, 0xbfb8aa3b, v33
	v_exp_f32_e32 v6, v6
	s_nop 0
	v_add_f32_e32 v6, 1.0, v6
	v_rcp_f32_e32 v6, v6
	s_nop 0
	v_mul_f32_e32 v6, v33, v6
	ds_write_b32 v2, v6 offset:13312
	v_mul_f32_e32 v6, 0xbfb8aa3b, v34
	v_exp_f32_e32 v6, v6
	s_nop 0
	v_add_f32_e32 v6, 1.0, v6
	v_rcp_f32_e32 v6, v6
	s_nop 0
	v_mul_f32_e32 v6, v34, v6
	ds_write_b32 v2, v6 offset:14336
	v_mul_f32_e32 v6, 0xbfb8aa3b, v35
	v_exp_f32_e32 v6, v6
	s_nop 0
	v_add_f32_e32 v6, 1.0, v6
	v_rcp_f32_e32 v6, v6
	s_nop 0
	v_mul_f32_e32 v6, v35, v6
	ds_write_b32 v2, v6 offset:15360
	v_mul_f32_e32 v6, 0xbfb8aa3b, v36
	v_exp_f32_e32 v6, v6
	s_nop 0
	v_add_f32_e32 v6, 1.0, v6
	v_rcp_f32_e32 v6, v6
	s_nop 0
	v_mul_f32_e32 v6, v36, v6
	ds_write_b32 v2, v6 offset:16384
	v_mul_f32_e32 v6, 0xbfb8aa3b, v37
	v_exp_f32_e32 v6, v6
	s_nop 0
	v_add_f32_e32 v6, 1.0, v6
	v_rcp_f32_e32 v6, v6
	s_nop 0
	v_mul_f32_e32 v6, v37, v6
	ds_write_b32 v2, v6 offset:17408
	v_mul_f32_e32 v6, 0xbfb8aa3b, v38
	v_exp_f32_e32 v6, v6
	s_nop 0
	v_add_f32_e32 v6, 1.0, v6
	v_rcp_f32_e32 v6, v6
	s_nop 0
	v_mul_f32_e32 v6, v38, v6
	ds_write_b32 v2, v6 offset:18432
	v_mul_f32_e32 v6, 0xbfb8aa3b, v39
	v_exp_f32_e32 v6, v6
	s_nop 0
	v_add_f32_e32 v6, 1.0, v6
	v_rcp_f32_e32 v6, v6
	s_nop 0
	v_mul_f32_e32 v6, v39, v6
	ds_write_b32 v2, v6 offset:19456
	v_and_b32_e32 v8, 15, v131
	v_lshrrev_b32_e32 v9, 4, v131
	v_lshlrev_b32_e32 v7, 8, v9
	v_mul_u32_u24_e32 v10, 0x180000, v9
	v_lshl_add_u32 v10, v8, 2, v10
	v_lshl_add_u32 v11, v9, 4, v8
	v_lshlrev_b32_e32 v11, 2, v11
	v_lshlrev_b32_e32 v12, 2, v8
	v_lshrrev_b32_e32 v13, 4, v131
	v_lshlrev_b32_e32 v16, 10, v13
	v_add_u32_e32 v16, v16, v12
	v_mul_u32_u24_e32 v17, 0x6000, v13
	v_add_u32_e32 v17, v17, v12
	s_movk_i32 s13, 0x6000
	v_readlane_b32 s12, v227, 0
	s_waitcnt lgkmcnt(0)
	s_barrier
.Lada2_loop:
	s_cmpk_ge_u32 s12, 0x600
	s_cbranch_scc1 .Lada2_done
	s_mov_b32 s2, 0
	s_cmpk_ge_u32 s12, 0x180
	s_addc_u32 s2, s2, 0
	s_cmpk_ge_u32 s12, 0x300
	s_addc_u32 s2, s2, 0
	s_cmpk_ge_u32 s12, 0x480
	s_addc_u32 s2, s2, 0
	s_mul_i32 s3, s2, 0x180
	s_sub_i32 s3, s12, s3
	s_lshl_b32 s3, s3, 6
	s_mul_i32 s6, s2, 0x1800000
	s_add_u32 s6, s6, s3
	s_add_u32 s6, s48, s6
	s_addc_u32 s7, s49, 0
	v_mov_b32_e32 v18, v10
	global_load_dword v20, v18, s[6:7]
	v_add_u32_e32 v18, s13, v18
	global_load_dword v21, v18, s[6:7]
	v_add_u32_e32 v18, s13, v18
	global_load_dword v22, v18, s[6:7]
	v_add_u32_e32 v18, s13, v18
	global_load_dword v23, v18, s[6:7]
	v_add_u32_e32 v18, s13, v18
	global_load_dword v24, v18, s[6:7]
	v_add_u32_e32 v18, s13, v18
	global_load_dword v25, v18, s[6:7]
	v_add_u32_e32 v18, s13, v18
	global_load_dword v26, v18, s[6:7]
	v_add_u32_e32 v18, s13, v18
	global_load_dword v27, v18, s[6:7]
	v_add_u32_e32 v18, s13, v18
	global_load_dword v28, v18, s[6:7]
	v_add_u32_e32 v18, s13, v18
	global_load_dword v29, v18, s[6:7]
	v_add_u32_e32 v18, s13, v18
	global_load_dword v30, v18, s[6:7]
	v_add_u32_e32 v18, s13, v18
	global_load_dword v31, v18, s[6:7]
	v_add_u32_e32 v18, s13, v18
	global_load_dword v32, v18, s[6:7]
	v_add_u32_e32 v18, s13, v18
	global_load_dword v33, v18, s[6:7]
	v_add_u32_e32 v18, s13, v18
	global_load_dword v34, v18, s[6:7]
	v_add_u32_e32 v18, s13, v18
	global_load_dword v35, v18, s[6:7]
	v_add_u32_e32 v18, s13, v18
	global_load_dword v36, v18, s[6:7]
	v_add_u32_e32 v18, s13, v18
	global_load_dword v37, v18, s[6:7]
	v_add_u32_e32 v18, s13, v18
	global_load_dword v38, v18, s[6:7]
	v_add_u32_e32 v18, s13, v18
	global_load_dword v39, v18, s[6:7]
	v_add_u32_e32 v18, s13, v18
	global_load_dword v40, v18, s[6:7]
	v_add_u32_e32 v18, s13, v18
	global_load_dword v41, v18, s[6:7]
	v_add_u32_e32 v18, s13, v18
	global_load_dword v42, v18, s[6:7]
	v_add_u32_e32 v18, s13, v18
	global_load_dword v43, v18, s[6:7]
	v_add_u32_e32 v18, s13, v18
	global_load_dword v44, v18, s[6:7]
	v_add_u32_e32 v18, s13, v18
	global_load_dword v45, v18, s[6:7]
	v_add_u32_e32 v18, s13, v18
	global_load_dword v46, v18, s[6:7]
	v_add_u32_e32 v18, s13, v18
	global_load_dword v47, v18, s[6:7]
	v_add_u32_e32 v18, s13, v18
	global_load_dword v48, v18, s[6:7]
	v_add_u32_e32 v18, s13, v18
	global_load_dword v49, v18, s[6:7]
	v_add_u32_e32 v18, s13, v18
	global_load_dword v50, v18, s[6:7]
	v_add_u32_e32 v18, s13, v18
	global_load_dword v51, v18, s[6:7]
	v_add_u32_e32 v18, s13, v18
	global_load_dword v52, v18, s[6:7]
	v_add_u32_e32 v18, s13, v18
	global_load_dword v53, v18, s[6:7]
	v_add_u32_e32 v18, s13, v18
	global_load_dword v54, v18, s[6:7]
	v_add_u32_e32 v18, s13, v18
	global_load_dword v55, v18, s[6:7]
	v_add_u32_e32 v18, s13, v18
	global_load_dword v56, v18, s[6:7]
	v_add_u32_e32 v18, s13, v18
	global_load_dword v57, v18, s[6:7]
	v_add_u32_e32 v18, s13, v18
	global_load_dword v58, v18, s[6:7]
	v_add_u32_e32 v18, s13, v18
	global_load_dword v59, v18, s[6:7]
	v_add_u32_e32 v18, s13, v18
	global_load_dword v60, v18, s[6:7]
	v_add_u32_e32 v18, s13, v18
	global_load_dword v61, v18, s[6:7]
	v_add_u32_e32 v18, s13, v18
	global_load_dword v62, v18, s[6:7]
	v_add_u32_e32 v18, s13, v18
	global_load_dword v63, v18, s[6:7]
	v_add_u32_e32 v18, s13, v18
	global_load_dword v64, v18, s[6:7]
	v_add_u32_e32 v18, s13, v18
	global_load_dword v65, v18, s[6:7]
	v_add_u32_e32 v18, s13, v18
	global_load_dword v66, v18, s[6:7]
	v_add_u32_e32 v18, s13, v18
	global_load_dword v67, v18, s[6:7]
	v_add_u32_e32 v18, s13, v18
	global_load_dword v68, v18, s[6:7]
	v_add_u32_e32 v18, s13, v18
	global_load_dword v69, v18, s[6:7]
	v_add_u32_e32 v18, s13, v18
	global_load_dword v70, v18, s[6:7]
	v_add_u32_e32 v18, s13, v18
	global_load_dword v71, v18, s[6:7]
	v_add_u32_e32 v18, s13, v18
	global_load_dword v72, v18, s[6:7]
	v_add_u32_e32 v18, s13, v18
	global_load_dword v73, v18, s[6:7]
	v_add_u32_e32 v18, s13, v18
	global_load_dword v74, v18, s[6:7]
	v_add_u32_e32 v18, s13, v18
	global_load_dword v75, v18, s[6:7]
	v_add_u32_e32 v18, s13, v18
	global_load_dword v76, v18, s[6:7]
	v_add_u32_e32 v18, s13, v18
	global_load_dword v77, v18, s[6:7]
	v_add_u32_e32 v18, s13, v18
	global_load_dword v78, v18, s[6:7]
	v_add_u32_e32 v18, s13, v18
	global_load_dword v79, v18, s[6:7]
	v_add_u32_e32 v18, s13, v18
	global_load_dword v80, v18, s[6:7]
	v_add_u32_e32 v18, s13, v18
	global_load_dword v81, v18, s[6:7]
	v_add_u32_e32 v18, s13, v18
	global_load_dword v82, v18, s[6:7]
	v_add_u32_e32 v18, s13, v18
	global_load_dword v83, v18, s[6:7]
	s_mul_i32 s8, s2, 0x6000
	s_add_u32 s8, s8, s3
	s_add_u32 s8, s50, s8
	s_addc_u32 s9, s51, 0
	s_mul_i32 s40, s2, 0x1e000
	s_add_u32 s40, s40, s3
	s_add_u32 s40, s42, s40
	s_addc_u32 s41, s43, 0
	v_mov_b32_e32 v104, 0
	v_mov_b32_e32 v105, 0
	v_mov_b32_e32 v106, 0
	v_mov_b32_e32 v107, 0
	v_mov_b32_e32 v108, 0
	s_waitcnt vmcnt(0)
	ds_read_b128 v[84:87], v7 offset:0
	ds_read_b128 v[88:91], v7 offset:4096
	ds_read_b128 v[92:95], v7 offset:8192
	ds_read_b128 v[96:99], v7 offset:12288
	ds_read_b128 v[100:103], v7 offset:16384
	s_waitcnt lgkmcnt(0)
	v_fmac_f32_e32 v104, v84, v20
	v_fmac_f32_e32 v105, v88, v20
	v_fmac_f32_e32 v106, v92, v20
	v_fmac_f32_e32 v107, v96, v20
	v_fmac_f32_e32 v108, v100, v20
	v_fmac_f32_e32 v104, v85, v21
	v_fmac_f32_e32 v105, v89, v21
	v_fmac_f32_e32 v106, v93, v21
	v_fmac_f32_e32 v107, v97, v21
	v_fmac_f32_e32 v108, v101, v21
	v_fmac_f32_e32 v104, v86, v22
	v_fmac_f32_e32 v105, v90, v22
	v_fmac_f32_e32 v106, v94, v22
	v_fmac_f32_e32 v107, v98, v22
	v_fmac_f32_e32 v108, v102, v22
	v_fmac_f32_e32 v104, v87, v23
	v_fmac_f32_e32 v105, v91, v23
	v_fmac_f32_e32 v106, v95, v23
	v_fmac_f32_e32 v107, v99, v23
	v_fmac_f32_e32 v108, v103, v23
	ds_read_b128 v[84:87], v7 offset:16
	ds_read_b128 v[88:91], v7 offset:4112
	ds_read_b128 v[92:95], v7 offset:8208
	ds_read_b128 v[96:99], v7 offset:12304
	ds_read_b128 v[100:103], v7 offset:16400
	s_waitcnt lgkmcnt(0)
	v_fmac_f32_e32 v104, v84, v24
	v_fmac_f32_e32 v105, v88, v24
	v_fmac_f32_e32 v106, v92, v24
	v_fmac_f32_e32 v107, v96, v24
	v_fmac_f32_e32 v108, v100, v24
	v_fmac_f32_e32 v104, v85, v25
	v_fmac_f32_e32 v105, v89, v25
	v_fmac_f32_e32 v106, v93, v25
	v_fmac_f32_e32 v107, v97, v25
	v_fmac_f32_e32 v108, v101, v25
	v_fmac_f32_e32 v104, v86, v26
	v_fmac_f32_e32 v105, v90, v26
	v_fmac_f32_e32 v106, v94, v26
	v_fmac_f32_e32 v107, v98, v26
	v_fmac_f32_e32 v108, v102, v26
	v_fmac_f32_e32 v104, v87, v27
	v_fmac_f32_e32 v105, v91, v27
	v_fmac_f32_e32 v106, v95, v27
	v_fmac_f32_e32 v107, v99, v27
	v_fmac_f32_e32 v108, v103, v27
	ds_read_b128 v[84:87], v7 offset:32
	ds_read_b128 v[88:91], v7 offset:4128
	ds_read_b128 v[92:95], v7 offset:8224
	ds_read_b128 v[96:99], v7 offset:12320
	ds_read_b128 v[100:103], v7 offset:16416
	s_waitcnt lgkmcnt(0)
	v_fmac_f32_e32 v104, v84, v28
	v_fmac_f32_e32 v105, v88, v28
	v_fmac_f32_e32 v106, v92, v28
	v_fmac_f32_e32 v107, v96, v28
	v_fmac_f32_e32 v108, v100, v28
	v_fmac_f32_e32 v104, v85, v29
	v_fmac_f32_e32 v105, v89, v29
	v_fmac_f32_e32 v106, v93, v29
	v_fmac_f32_e32 v107, v97, v29
	v_fmac_f32_e32 v108, v101, v29
	v_fmac_f32_e32 v104, v86, v30
	v_fmac_f32_e32 v105, v90, v30
	v_fmac_f32_e32 v106, v94, v30
	v_fmac_f32_e32 v107, v98, v30
	v_fmac_f32_e32 v108, v102, v30
	v_fmac_f32_e32 v104, v87, v31
	v_fmac_f32_e32 v105, v91, v31
	v_fmac_f32_e32 v106, v95, v31
	v_fmac_f32_e32 v107, v99, v31
	v_fmac_f32_e32 v108, v103, v31
	ds_read_b128 v[84:87], v7 offset:48
	ds_read_b128 v[88:91], v7 offset:4144
	ds_read_b128 v[92:95], v7 offset:8240
	ds_read_b128 v[96:99], v7 offset:12336
	ds_read_b128 v[100:103], v7 offset:16432
	s_waitcnt lgkmcnt(0)
	v_fmac_f32_e32 v104, v84, v32
	v_fmac_f32_e32 v105, v88, v32
	v_fmac_f32_e32 v106, v92, v32
	v_fmac_f32_e32 v107, v96, v32
	v_fmac_f32_e32 v108, v100, v32
	v_fmac_f32_e32 v104, v85, v33
	v_fmac_f32_e32 v105, v89, v33
	v_fmac_f32_e32 v106, v93, v33
	v_fmac_f32_e32 v107, v97, v33
	v_fmac_f32_e32 v108, v101, v33
	v_fmac_f32_e32 v104, v86, v34
	v_fmac_f32_e32 v105, v90, v34
	v_fmac_f32_e32 v106, v94, v34
	v_fmac_f32_e32 v107, v98, v34
	v_fmac_f32_e32 v108, v102, v34
	v_fmac_f32_e32 v104, v87, v35
	v_fmac_f32_e32 v105, v91, v35
	v_fmac_f32_e32 v106, v95, v35
	v_fmac_f32_e32 v107, v99, v35
	v_fmac_f32_e32 v108, v103, v35
	ds_read_b128 v[84:87], v7 offset:64
	ds_read_b128 v[88:91], v7 offset:4160
	ds_read_b128 v[92:95], v7 offset:8256
	ds_read_b128 v[96:99], v7 offset:12352
	ds_read_b128 v[100:103], v7 offset:16448
	s_waitcnt lgkmcnt(0)
	v_fmac_f32_e32 v104, v84, v36
	v_fmac_f32_e32 v105, v88, v36
	v_fmac_f32_e32 v106, v92, v36
	v_fmac_f32_e32 v107, v96, v36
	v_fmac_f32_e32 v108, v100, v36
	v_fmac_f32_e32 v104, v85, v37
	v_fmac_f32_e32 v105, v89, v37
	v_fmac_f32_e32 v106, v93, v37
	v_fmac_f32_e32 v107, v97, v37
	v_fmac_f32_e32 v108, v101, v37
	v_fmac_f32_e32 v104, v86, v38
	v_fmac_f32_e32 v105, v90, v38
	v_fmac_f32_e32 v106, v94, v38
	v_fmac_f32_e32 v107, v98, v38
	v_fmac_f32_e32 v108, v102, v38
	v_fmac_f32_e32 v104, v87, v39
	v_fmac_f32_e32 v105, v91, v39
	v_fmac_f32_e32 v106, v95, v39
	v_fmac_f32_e32 v107, v99, v39
	v_fmac_f32_e32 v108, v103, v39
	ds_read_b128 v[84:87], v7 offset:80
	ds_read_b128 v[88:91], v7 offset:4176
	ds_read_b128 v[92:95], v7 offset:8272
	ds_read_b128 v[96:99], v7 offset:12368
	ds_read_b128 v[100:103], v7 offset:16464
	s_waitcnt lgkmcnt(0)
	v_fmac_f32_e32 v104, v84, v40
	v_fmac_f32_e32 v105, v88, v40
	v_fmac_f32_e32 v106, v92, v40
	v_fmac_f32_e32 v107, v96, v40
	v_fmac_f32_e32 v108, v100, v40
	v_fmac_f32_e32 v104, v85, v41
	v_fmac_f32_e32 v105, v89, v41
	v_fmac_f32_e32 v106, v93, v41
	v_fmac_f32_e32 v107, v97, v41
	v_fmac_f32_e32 v108, v101, v41
	v_fmac_f32_e32 v104, v86, v42
	v_fmac_f32_e32 v105, v90, v42
	v_fmac_f32_e32 v106, v94, v42
	v_fmac_f32_e32 v107, v98, v42
	v_fmac_f32_e32 v108, v102, v42
	v_fmac_f32_e32 v104, v87, v43
	v_fmac_f32_e32 v105, v91, v43
	v_fmac_f32_e32 v106, v95, v43
	v_fmac_f32_e32 v107, v99, v43
	v_fmac_f32_e32 v108, v103, v43
	ds_read_b128 v[84:87], v7 offset:96
	ds_read_b128 v[88:91], v7 offset:4192
	ds_read_b128 v[92:95], v7 offset:8288
	ds_read_b128 v[96:99], v7 offset:12384
	ds_read_b128 v[100:103], v7 offset:16480
	s_waitcnt lgkmcnt(0)
	v_fmac_f32_e32 v104, v84, v44
	v_fmac_f32_e32 v105, v88, v44
	v_fmac_f32_e32 v106, v92, v44
	v_fmac_f32_e32 v107, v96, v44
	v_fmac_f32_e32 v108, v100, v44
	v_fmac_f32_e32 v104, v85, v45
	v_fmac_f32_e32 v105, v89, v45
	v_fmac_f32_e32 v106, v93, v45
	v_fmac_f32_e32 v107, v97, v45
	v_fmac_f32_e32 v108, v101, v45
	v_fmac_f32_e32 v104, v86, v46
	v_fmac_f32_e32 v105, v90, v46
	v_fmac_f32_e32 v106, v94, v46
	v_fmac_f32_e32 v107, v98, v46
	v_fmac_f32_e32 v108, v102, v46
	v_fmac_f32_e32 v104, v87, v47
	v_fmac_f32_e32 v105, v91, v47
	v_fmac_f32_e32 v106, v95, v47
	v_fmac_f32_e32 v107, v99, v47
	v_fmac_f32_e32 v108, v103, v47
	ds_read_b128 v[84:87], v7 offset:112
	ds_read_b128 v[88:91], v7 offset:4208
	ds_read_b128 v[92:95], v7 offset:8304
	ds_read_b128 v[96:99], v7 offset:12400
	ds_read_b128 v[100:103], v7 offset:16496
	s_waitcnt lgkmcnt(0)
	v_fmac_f32_e32 v104, v84, v48
	v_fmac_f32_e32 v105, v88, v48
	v_fmac_f32_e32 v106, v92, v48
	v_fmac_f32_e32 v107, v96, v48
	v_fmac_f32_e32 v108, v100, v48
	v_fmac_f32_e32 v104, v85, v49
	v_fmac_f32_e32 v105, v89, v49
	v_fmac_f32_e32 v106, v93, v49
	v_fmac_f32_e32 v107, v97, v49
	v_fmac_f32_e32 v108, v101, v49
	v_fmac_f32_e32 v104, v86, v50
	v_fmac_f32_e32 v105, v90, v50
	v_fmac_f32_e32 v106, v94, v50
	v_fmac_f32_e32 v107, v98, v50
	v_fmac_f32_e32 v108, v102, v50
	v_fmac_f32_e32 v104, v87, v51
	v_fmac_f32_e32 v105, v91, v51
	v_fmac_f32_e32 v106, v95, v51
	v_fmac_f32_e32 v107, v99, v51
	v_fmac_f32_e32 v108, v103, v51
	ds_read_b128 v[84:87], v7 offset:128
	ds_read_b128 v[88:91], v7 offset:4224
	ds_read_b128 v[92:95], v7 offset:8320
	ds_read_b128 v[96:99], v7 offset:12416
	ds_read_b128 v[100:103], v7 offset:16512
	s_waitcnt lgkmcnt(0)
	v_fmac_f32_e32 v104, v84, v52
	v_fmac_f32_e32 v105, v88, v52
	v_fmac_f32_e32 v106, v92, v52
	v_fmac_f32_e32 v107, v96, v52
	v_fmac_f32_e32 v108, v100, v52
	v_fmac_f32_e32 v104, v85, v53
	v_fmac_f32_e32 v105, v89, v53
	v_fmac_f32_e32 v106, v93, v53
	v_fmac_f32_e32 v107, v97, v53
	v_fmac_f32_e32 v108, v101, v53
	v_fmac_f32_e32 v104, v86, v54
	v_fmac_f32_e32 v105, v90, v54
	v_fmac_f32_e32 v106, v94, v54
	v_fmac_f32_e32 v107, v98, v54
	v_fmac_f32_e32 v108, v102, v54
	v_fmac_f32_e32 v104, v87, v55
	v_fmac_f32_e32 v105, v91, v55
	v_fmac_f32_e32 v106, v95, v55
	v_fmac_f32_e32 v107, v99, v55
	v_fmac_f32_e32 v108, v103, v55
	ds_read_b128 v[84:87], v7 offset:144
	ds_read_b128 v[88:91], v7 offset:4240
	ds_read_b128 v[92:95], v7 offset:8336
	ds_read_b128 v[96:99], v7 offset:12432
	ds_read_b128 v[100:103], v7 offset:16528
	s_waitcnt lgkmcnt(0)
	v_fmac_f32_e32 v104, v84, v56
	v_fmac_f32_e32 v105, v88, v56
	v_fmac_f32_e32 v106, v92, v56
	v_fmac_f32_e32 v107, v96, v56
	v_fmac_f32_e32 v108, v100, v56
	v_fmac_f32_e32 v104, v85, v57
	v_fmac_f32_e32 v105, v89, v57
	v_fmac_f32_e32 v106, v93, v57
	v_fmac_f32_e32 v107, v97, v57
	v_fmac_f32_e32 v108, v101, v57
	v_fmac_f32_e32 v104, v86, v58
	v_fmac_f32_e32 v105, v90, v58
	v_fmac_f32_e32 v106, v94, v58
	v_fmac_f32_e32 v107, v98, v58
	v_fmac_f32_e32 v108, v102, v58
	v_fmac_f32_e32 v104, v87, v59
	v_fmac_f32_e32 v105, v91, v59
	v_fmac_f32_e32 v106, v95, v59
	v_fmac_f32_e32 v107, v99, v59
	v_fmac_f32_e32 v108, v103, v59
	ds_read_b128 v[84:87], v7 offset:160
	ds_read_b128 v[88:91], v7 offset:4256
	ds_read_b128 v[92:95], v7 offset:8352
	ds_read_b128 v[96:99], v7 offset:12448
	ds_read_b128 v[100:103], v7 offset:16544
	s_waitcnt lgkmcnt(0)
	v_fmac_f32_e32 v104, v84, v60
	v_fmac_f32_e32 v105, v88, v60
	v_fmac_f32_e32 v106, v92, v60
	v_fmac_f32_e32 v107, v96, v60
	v_fmac_f32_e32 v108, v100, v60
	v_fmac_f32_e32 v104, v85, v61
	v_fmac_f32_e32 v105, v89, v61
	v_fmac_f32_e32 v106, v93, v61
	v_fmac_f32_e32 v107, v97, v61
	v_fmac_f32_e32 v108, v101, v61
	v_fmac_f32_e32 v104, v86, v62
	v_fmac_f32_e32 v105, v90, v62
	v_fmac_f32_e32 v106, v94, v62
	v_fmac_f32_e32 v107, v98, v62
	v_fmac_f32_e32 v108, v102, v62
	v_fmac_f32_e32 v104, v87, v63
	v_fmac_f32_e32 v105, v91, v63
	v_fmac_f32_e32 v106, v95, v63
	v_fmac_f32_e32 v107, v99, v63
	v_fmac_f32_e32 v108, v103, v63
	ds_read_b128 v[84:87], v7 offset:176
	ds_read_b128 v[88:91], v7 offset:4272
	ds_read_b128 v[92:95], v7 offset:8368
	ds_read_b128 v[96:99], v7 offset:12464
	ds_read_b128 v[100:103], v7 offset:16560
	s_waitcnt lgkmcnt(0)
	v_fmac_f32_e32 v104, v84, v64
	v_fmac_f32_e32 v105, v88, v64
	v_fmac_f32_e32 v106, v92, v64
	v_fmac_f32_e32 v107, v96, v64
	v_fmac_f32_e32 v108, v100, v64
	v_fmac_f32_e32 v104, v85, v65
	v_fmac_f32_e32 v105, v89, v65
	v_fmac_f32_e32 v106, v93, v65
	v_fmac_f32_e32 v107, v97, v65
	v_fmac_f32_e32 v108, v101, v65
	v_fmac_f32_e32 v104, v86, v66
	v_fmac_f32_e32 v105, v90, v66
	v_fmac_f32_e32 v106, v94, v66
	v_fmac_f32_e32 v107, v98, v66
	v_fmac_f32_e32 v108, v102, v66
	v_fmac_f32_e32 v104, v87, v67
	v_fmac_f32_e32 v105, v91, v67
	v_fmac_f32_e32 v106, v95, v67
	v_fmac_f32_e32 v107, v99, v67
	v_fmac_f32_e32 v108, v103, v67
	ds_read_b128 v[84:87], v7 offset:192
	ds_read_b128 v[88:91], v7 offset:4288
	ds_read_b128 v[92:95], v7 offset:8384
	ds_read_b128 v[96:99], v7 offset:12480
	ds_read_b128 v[100:103], v7 offset:16576
	s_waitcnt lgkmcnt(0)
	v_fmac_f32_e32 v104, v84, v68
	v_fmac_f32_e32 v105, v88, v68
	v_fmac_f32_e32 v106, v92, v68
	v_fmac_f32_e32 v107, v96, v68
	v_fmac_f32_e32 v108, v100, v68
	v_fmac_f32_e32 v104, v85, v69
	v_fmac_f32_e32 v105, v89, v69
	v_fmac_f32_e32 v106, v93, v69
	v_fmac_f32_e32 v107, v97, v69
	v_fmac_f32_e32 v108, v101, v69
	v_fmac_f32_e32 v104, v86, v70
	v_fmac_f32_e32 v105, v90, v70
	v_fmac_f32_e32 v106, v94, v70
	v_fmac_f32_e32 v107, v98, v70
	v_fmac_f32_e32 v108, v102, v70
	v_fmac_f32_e32 v104, v87, v71
	v_fmac_f32_e32 v105, v91, v71
	v_fmac_f32_e32 v106, v95, v71
	v_fmac_f32_e32 v107, v99, v71
	v_fmac_f32_e32 v108, v103, v71
	ds_read_b128 v[84:87], v7 offset:208
	ds_read_b128 v[88:91], v7 offset:4304
	ds_read_b128 v[92:95], v7 offset:8400
	ds_read_b128 v[96:99], v7 offset:12496
	ds_read_b128 v[100:103], v7 offset:16592
	s_waitcnt lgkmcnt(0)
	v_fmac_f32_e32 v104, v84, v72
	v_fmac_f32_e32 v105, v88, v72
	v_fmac_f32_e32 v106, v92, v72
	v_fmac_f32_e32 v107, v96, v72
	v_fmac_f32_e32 v108, v100, v72
	v_fmac_f32_e32 v104, v85, v73
	v_fmac_f32_e32 v105, v89, v73
	v_fmac_f32_e32 v106, v93, v73
	v_fmac_f32_e32 v107, v97, v73
	v_fmac_f32_e32 v108, v101, v73
	v_fmac_f32_e32 v104, v86, v74
	v_fmac_f32_e32 v105, v90, v74
	v_fmac_f32_e32 v106, v94, v74
	v_fmac_f32_e32 v107, v98, v74
	v_fmac_f32_e32 v108, v102, v74
	v_fmac_f32_e32 v104, v87, v75
	v_fmac_f32_e32 v105, v91, v75
	v_fmac_f32_e32 v106, v95, v75
	v_fmac_f32_e32 v107, v99, v75
	v_fmac_f32_e32 v108, v103, v75
	ds_read_b128 v[84:87], v7 offset:224
	ds_read_b128 v[88:91], v7 offset:4320
	ds_read_b128 v[92:95], v7 offset:8416
	ds_read_b128 v[96:99], v7 offset:12512
	ds_read_b128 v[100:103], v7 offset:16608
	s_waitcnt lgkmcnt(0)
	v_fmac_f32_e32 v104, v84, v76
	v_fmac_f32_e32 v105, v88, v76
	v_fmac_f32_e32 v106, v92, v76
	v_fmac_f32_e32 v107, v96, v76
	v_fmac_f32_e32 v108, v100, v76
	v_fmac_f32_e32 v104, v85, v77
	v_fmac_f32_e32 v105, v89, v77
	v_fmac_f32_e32 v106, v93, v77
	v_fmac_f32_e32 v107, v97, v77
	v_fmac_f32_e32 v108, v101, v77
	v_fmac_f32_e32 v104, v86, v78
	v_fmac_f32_e32 v105, v90, v78
	v_fmac_f32_e32 v106, v94, v78
	v_fmac_f32_e32 v107, v98, v78
	v_fmac_f32_e32 v108, v102, v78
	v_fmac_f32_e32 v104, v87, v79
	v_fmac_f32_e32 v105, v91, v79
	v_fmac_f32_e32 v106, v95, v79
	v_fmac_f32_e32 v107, v99, v79
	v_fmac_f32_e32 v108, v103, v79
	ds_read_b128 v[84:87], v7 offset:240
	ds_read_b128 v[88:91], v7 offset:4336
	ds_read_b128 v[92:95], v7 offset:8432
	ds_read_b128 v[96:99], v7 offset:12528
	ds_read_b128 v[100:103], v7 offset:16624
	s_waitcnt lgkmcnt(0)
	v_fmac_f32_e32 v104, v84, v80
	v_fmac_f32_e32 v105, v88, v80
	v_fmac_f32_e32 v106, v92, v80
	v_fmac_f32_e32 v107, v96, v80
	v_fmac_f32_e32 v108, v100, v80
	v_fmac_f32_e32 v104, v85, v81
	v_fmac_f32_e32 v105, v89, v81
	v_fmac_f32_e32 v106, v93, v81
	v_fmac_f32_e32 v107, v97, v81
	v_fmac_f32_e32 v108, v101, v81
	v_fmac_f32_e32 v104, v86, v82
	v_fmac_f32_e32 v105, v90, v82
	v_fmac_f32_e32 v106, v94, v82
	v_fmac_f32_e32 v107, v98, v82
	v_fmac_f32_e32 v108, v102, v82
	v_fmac_f32_e32 v104, v87, v83
	v_fmac_f32_e32 v105, v91, v83
	v_fmac_f32_e32 v106, v95, v83
	v_fmac_f32_e32 v107, v99, v83
	v_fmac_f32_e32 v108, v103, v83
	ds_write_b32 v11, v104 offset:20480
	ds_write_b32 v11, v105 offset:21504
	ds_write_b32 v11, v106 offset:22528
	ds_write_b32 v11, v107 offset:23552
	ds_write_b32 v11, v108 offset:24576
	s_waitcnt lgkmcnt(0)
	s_barrier
	v_cmp_gt_u32_e32 vcc, 0x50, v131
	s_and_saveexec_b64 s[44:45], vcc
	s_cbranch_execz .Lada2_skip
	global_load_dword v19, v12, s[8:9]
	ds_read_b32 v20, v16 offset:20480
	ds_read_b32 v21, v16 offset:20544
	ds_read_b32 v22, v16 offset:20608
	ds_read_b32 v23, v16 offset:20672
	ds_read_b32 v24, v16 offset:20736
	ds_read_b32 v25, v16 offset:20800
	ds_read_b32 v26, v16 offset:20864
	ds_read_b32 v27, v16 offset:20928
	ds_read_b32 v28, v16 offset:20992
	ds_read_b32 v29, v16 offset:21056
	ds_read_b32 v30, v16 offset:21120
	ds_read_b32 v31, v16 offset:21184
	ds_read_b32 v32, v16 offset:21248
	ds_read_b32 v33, v16 offset:21312
	ds_read_b32 v34, v16 offset:21376
	ds_read_b32 v35, v16 offset:21440
	s_waitcnt lgkmcnt(0)
	v_add_f32_e32 v20, v20, v21
	v_add_f32_e32 v20, v20, v22
	v_add_f32_e32 v20, v20, v23
	v_add_f32_e32 v20, v20, v24
	v_add_f32_e32 v20, v20, v25
	v_add_f32_e32 v20, v20, v26
	v_add_f32_e32 v20, v20, v27
	v_add_f32_e32 v20, v20, v28
	v_add_f32_e32 v20, v20, v29
	v_add_f32_e32 v20, v20, v30
	v_add_f32_e32 v20, v20, v31
	v_add_f32_e32 v20, v20, v32
	v_add_f32_e32 v20, v20, v33
	v_add_f32_e32 v20, v20, v34
	v_add_f32_e32 v20, v20, v35
	s_waitcnt vmcnt(0)
	v_add_f32_e32 v20, v20, v19
	global_store_dword v17, v20, s[40:41]
.Lada2_skip:
	s_or_b64 exec, exec, s[44:45]
	s_barrier
	s_addk_i32 s12, 0x200
	s_branch .Lada2_loop
.Lada2_done:
	s_waitcnt vmcnt(0)
	s_branch .LBB0_701
	v_readlane_b32 s6, v224, 34
	v_readlane_b32 s7, v224, 35
	s_load_dwordx8 s[44:51], s[6:7], 0x28
	s_movk_i32 s2, 0x1400
	v_cmp_gt_i32_e32 vcc, s2, v15
	s_load_dwordx2 s[2:3], s[6:7], 0x1b0
	v_ashrrev_i32_e32 v4, 6, v15
	s_movk_i32 s6, 0x500
	v_lshlrev_b32_e32 v5, 8, v4
	s_waitcnt lgkmcnt(0)
	v_mov_b32_e32 v2, s48
	v_mov_b32_e32 v3, s49
	v_mul_lo_u32 v6, v4, s6
	v_lshlrev_b32_e32 v0, 2, v14
	s_movk_i32 s6, 0x140
	v_lshlrev_b32_e32 v29, 2, v15
	v_or_b32_e32 v28, v6, v0
	v_cmp_gt_i32_e64 s[40:41], s6, v15
	v_lshl_add_u64 v[16:17], s[2:3], 0, v[0:1]
	v_mad_i64_i32 v[18:19], s[2:3], v5, s81, v[2:3]
	v_lshlrev_b32_e32 v30, 10, v4
	v_add_u32_e32 v31, 0x5000, v29
	v_readlane_b32 s12, v227, 0
	s_branch .LBB0_689
